# convert_weights transposing blocks: the four row loads issued together (addresses recomputed into unused registers), counted vmcnt(3/2/1/0) before the LDS writes
# speedup vs baseline: 1.0065x; 1.0065x over previous
; DI unsigned pk2(float a, float b) { f32x2_t f = {a, b}; return __builtin_bit_cast(unsigned, __builtin_convertvector(f, bf16x2_t)); }
; DI void tconv_tile(const float* __restrict__ src, long lds, int cvalid, u16* __restrict__ dst, long ldd, int r0, int c0, char* smem) {
;     ...
;   __syncthreads();
;   const int lr = tid >> 4, lc = (tid & 15) * 4;
; #pragma unroll
;   for (int i = 0; i < 4; ++i) {
;     const int r = lr + 16 * i;
;     float4 v = make_float4(0.f, 0.f, 0.f, 0.f);
;     if (c0 + lc < cvalid) v = *(const float4*)(src + (long)(r0 + r) * lds + c0 + lc);
;     T[r][lc] = v.x; T[r][lc + 1] = v.y; T[r][lc + 2] = v.z; T[r][lc + 3] = v.w;
;   }
;   __syncthreads();
;   const int oc = tid >> 2, seg = (tid & 3) * 16;
;   unsigned pk[8];
; #pragma unroll
;   for (int k = 0; k < 8; ++k) pk[k] = pk2(T[seg + 2 * k][oc], T[seg + 2 * k + 1][oc]);
;   uint4* d = (uint4*)(dst + (long)(c0 + oc) * ldd + r0 + seg);
;   d[0] = make_uint4(pk[0], pk[1], pk[2], pk[3]);
;   d[1] = make_uint4(pk[4], pk[5], pk[6], pk[7]);
; DI void convert_weights(const Params& p, int layer, char* smem) {
;     ...
;       } else if (t < 592) {
;         const int u = t - 448;
;         tconv_tile(p.w_q_up + (size_t)o * 384 * 1536, 1536, 1536, W + WO_Q, 384, (u / 24) * 64, (u % 24) * 64, smem);
.LBB0_269:
	s_andn2_b64 vcc, exec, s[38:39]
	s_cbranch_vccnz .LBB0_271
	s_add_i32 s14, s4, 64
	s_and_b32 s13, s14, 0xff
	s_mulk_i32 s13, 0xab
	s_bfe_u32 s13, s13, 0x4000c
	s_mul_i32 s15, s13, 24
	s_sub_i32 s14, s14, s15
	s_and_b32 s16, s14, 0xff
	v_mov_b32_e32 v9, v185
	s_lshl_b32 s14, s16, 8
	v_readlane_b32 s15, v253, 3
	s_add_u32 s14, s15, s14
	v_lshlrev_b32_e32 v12, 4, v9
	v_readlane_b32 s15, v253, 4
	v_ashrrev_i32_e32 v4, 4, v9
	v_and_b32_e32 v182, 0xf0, v12
	s_addc_u32 s15, s15, 0
	v_lshl_add_u64 v[6:7], s[14:15], 0, v[182:183]
	v_lshl_add_u32 v13, s13, 6, v4
	s_movk_i32 s18, 0x1800
	v_mad_i64_i32 v[2:3], s[14:15], v13, s18, v[6:7]
	s_movk_i32 s17, 0x104
	s_barrier
	global_load_dwordx4 v[100:103], v[2:3], off
	v_add_u32_e32 v152, 16, v13
	v_mad_i64_i32 v[134:135], s[14:15], v152, s18, v[6:7]
	global_load_dwordx4 v[136:139], v[134:135], off
	v_add_u32_e32 v153, 32, v13
	v_mad_i64_i32 v[148:149], s[14:15], v153, s18, v[6:7]
	global_load_dwordx4 v[140:143], v[148:149], off
	v_add_u32_e32 v154, 48, v13
	v_mad_i64_i32 v[150:151], s[14:15], v154, s18, v[6:7]
	global_load_dwordx4 v[144:147], v[150:151], off
	v_mad_u64_u32 v[10:11], s[14:15], v4, s17, v[182:183]
	s_nop 0
	v_add_u32_e32 v11, 0x1040, v10
	v_and_b32_e32 v15, 48, v12
	v_ashrrev_i32_e32 v14, 2, v9
	s_lshl_b32 s34, s13, 7
	v_lshlrev_b32_e32 v182, 1, v15
	s_waitcnt vmcnt(3)
	ds_write2_b32 v10, v100, v101 offset1:1
	ds_write2_b32 v10, v102, v103 offset0:2 offset1:3
	v_add_u32_e32 v2, 16, v13
	s_waitcnt vmcnt(2)
	ds_write2_b32 v11, v136, v137 offset1:1
	v_add_u32_e32 v2, 0x1048, v10
	ds_write2_b32 v2, v138, v139 offset1:1
	v_add_u32_e32 v2, 32, v13
	v_add_u32_e32 v11, 0x2080, v10
	s_waitcnt vmcnt(1)
	ds_write2_b32 v11, v140, v141 offset1:1
	v_add_u32_e32 v2, 0x2088, v10
	ds_write2_b32 v2, v142, v143 offset1:1
	v_add_u32_e32 v2, 48, v13
	v_add_u32_e32 v6, 0x30c0, v10
	v_readlane_b32 s14, v252, 29
	v_readlane_b32 s15, v252, 30
	s_waitcnt vmcnt(0)
	ds_write2_b32 v6, v144, v145 offset1:1
	v_add_u32_e32 v2, 0x30c8, v10
	ds_write2_b32 v2, v146, v147 offset1:1
	v_and_b32_e32 v2, -4, v9
	v_mad_u32_u24 v9, v15, s17, v2
	s_waitcnt lgkmcnt(0)
	s_barrier
	ds_read2_b32 v[2:3], v9 offset1:65
	ds_read2_b32 v[4:5], v9 offset0:130 offset1:195
	v_add_u32_e32 v6, 0x400, v9
	v_add_u32_e32 v11, 0x800, v9
	v_add_u32_e32 v9, 0xc00, v9
	s_waitcnt lgkmcnt(1)
	v_cvt_pk_bf16_f32 v2, v2, v3
	s_waitcnt lgkmcnt(0)
	v_cvt_pk_bf16_f32 v3, v4, v5
	ds_read2_b32 v[4:5], v6 offset0:4 offset1:69
	ds_read2_b32 v[6:7], v6 offset0:134 offset1:199
	s_waitcnt lgkmcnt(1)
	v_cvt_pk_bf16_f32 v4, v4, v5
	s_waitcnt lgkmcnt(0)
	v_cvt_pk_bf16_f32 v5, v6, v7
	ds_read2_b32 v[6:7], v11 offset0:8 offset1:73
	s_waitcnt lgkmcnt(0)
	v_cvt_pk_bf16_f32 v10, v6, v7
	ds_read2_b32 v[6:7], v11 offset0:138 offset1:203
	s_waitcnt lgkmcnt(0)
	v_cvt_pk_bf16_f32 v11, v6, v7
	ds_read2_b32 v[6:7], v9 offset0:12 offset1:77
	s_waitcnt lgkmcnt(0)
	v_cvt_pk_bf16_f32 v12, v6, v7
	ds_read2_b32 v[6:7], v9 offset0:142 offset1:207
	v_lshl_add_u32 v9, s16, 6, v14
	s_waitcnt lgkmcnt(0)
	v_cvt_pk_bf16_f32 v13, v6, v7
	v_mov_b64_e32 v[6:7], s[14:15]
	s_movk_i32 s14, 0x300
	v_mad_i64_i32 v[6:7], s[14:15], v9, s14, v[6:7]
	v_lshl_add_u64 v[6:7], v[6:7], 0, s[34:35]
	v_lshl_add_u64 v[6:7], v[6:7], 0, v[182:183]
	global_store_dwordx4 v[6:7], v[2:5], off
	global_store_dwordx4 v[6:7], v[10:13], off offset:16

; DI int get_bid() { int b = blockIdx.x; asm volatile("" : "+s"(b)); return b; }
; DI unsigned pk2(float a, float b) { f32x2_t f = {a, b}; return __builtin_bit_cast(unsigned, __builtin_convertvector(f, bf16x2_t)); }
; DI void tconv_tile(const float* __restrict__ src, long lds, int cvalid, u16* __restrict__ dst, long ldd, int r0, int c0, char* smem) {
;     ...
;   __syncthreads();
;   const int lr = tid >> 4, lc = (tid & 15) * 4;
; #pragma unroll
;   for (int i = 0; i < 4; ++i) {
;     const int r = lr + 16 * i;
;     float4 v = make_float4(0.f, 0.f, 0.f, 0.f);
;     if (c0 + lc < cvalid) v = *(const float4*)(src + (long)(r0 + r) * lds + c0 + lc);
;     T[r][lc] = v.x; T[r][lc + 1] = v.y; T[r][lc + 2] = v.z; T[r][lc + 3] = v.w;
;   }
;   __syncthreads();
;   const int oc = tid >> 2, seg = (tid & 3) * 16;
;   unsigned pk[8];
; #pragma unroll
;   for (int k = 0; k < 8; ++k) pk[k] = pk2(T[seg + 2 * k][oc], T[seg + 2 * k + 1][oc]);
;   uint4* d = (uint4*)(dst + (long)(c0 + oc) * ldd + r0 + seg);
;   d[0] = make_uint4(pk[0], pk[1], pk[2], pk[3]);
;   d[1] = make_uint4(pk[4], pk[5], pk[6], pk[7]);
; DI void convert_weights(const Params& p, int layer, char* smem) {
;     ...
;     for (int t = get_bid(); t < 1920; t += gridDim.x) {
;       if (t < 1280) {
;         tconv_tile(p.w_in_even + (size_t)e * 1024 * 5120, 5120, 5120, W + WE_IN, 1024, (t / 80) * 64, (t % 80) * 64, smem);
.LBB0_895:
	s_andn2_b64 vcc, exec, s[38:39]
	s_cbranch_vccnz .LBB0_884
	s_mul_hi_i32 s11, s4, 0x66666667
	s_lshr_b32 s12, s11, 31
	s_ashr_i32 s11, s11, 5
	s_add_i32 s11, s11, s12
	s_mul_i32 s12, s11, 0xffffec00
	s_add_i32 s12, s5, s12
	s_ashr_i32 s13, s12, 31
	s_lshl_b32 s38, s11, 6
	v_mov_b32_e32 v1, v185
	s_lshl_b64 s[12:13], s[12:13], 2
	v_readlane_b32 s14, v253, 15
	s_add_u32 s12, s14, s12
	v_lshlrev_b32_e32 v12, 4, v1
	v_readlane_b32 s14, v253, 16
	v_ashrrev_i32_e32 v3, 4, v1
	v_and_b32_e32 v182, 0xf0, v12
	s_addc_u32 s13, s14, s13
	v_lshl_add_u64 v[8:9], s[12:13], 0, v[182:183]
	v_add_u32_e32 v13, s38, v3
	s_movk_i32 s15, 0x5000
	v_mad_i64_i32 v[4:5], s[12:13], v13, s15, v[8:9]
	s_barrier
	global_load_dwordx4 v[100:103], v[4:5], off
	v_add_u32_e32 v152, 16, v13
	v_mad_i64_i32 v[134:135], s[12:13], v152, s15, v[8:9]
	global_load_dwordx4 v[136:139], v[134:135], off
	v_add_u32_e32 v153, 32, v13
	v_mad_i64_i32 v[148:149], s[12:13], v153, s15, v[8:9]
	global_load_dwordx4 v[140:143], v[148:149], off
	v_add_u32_e32 v154, 48, v13
	v_mad_i64_i32 v[150:151], s[12:13], v154, s15, v[8:9]
	global_load_dwordx4 v[144:147], v[150:151], off
	s_nop 0
	s_movk_i32 s14, 0x104
	v_mad_u64_u32 v[10:11], s[12:13], v3, s14, v[182:183]
	v_add_u32_e32 v3, 16, v13
	v_and_b32_e32 v14, 48, v12
	s_mulk_i32 s11, 0x1400
	s_ashr_i32 s39, s38, 31
	v_lshlrev_b32_e32 v182, 1, v14
	s_waitcnt vmcnt(3)
	ds_write2_b32 v10, v100, v101 offset1:1
	ds_write2_b32 v10, v102, v103 offset0:2 offset1:3
	v_add_u32_e32 v3, 0x1040, v10
	s_waitcnt vmcnt(2)
	ds_write2_b32 v3, v136, v137 offset1:1
	v_add_u32_e32 v3, 0x1048, v10
	ds_write2_b32 v3, v138, v139 offset1:1
	v_add_u32_e32 v3, 32, v13
	v_add_u32_e32 v3, 0x2080, v10
	s_waitcnt vmcnt(1)
	ds_write2_b32 v3, v140, v141 offset1:1
	v_add_u32_e32 v3, 0x2088, v10
	ds_write2_b32 v3, v142, v143 offset1:1
	v_add_u32_e32 v3, 48, v13
	v_add_u32_e32 v3, 0x30c0, v10
	s_waitcnt vmcnt(0)
	ds_write2_b32 v3, v144, v145 offset1:1
	v_add_u32_e32 v3, 0x30c8, v10
	ds_write2_b32 v3, v146, v147 offset1:1
	v_ashrrev_i32_e32 v3, 2, v1
	v_and_b32_e32 v1, -4, v1
	v_mad_u32_u24 v1, v14, s14, v1
	s_waitcnt lgkmcnt(0)
	s_barrier
	ds_read2_b32 v[4:5], v1 offset1:65
	ds_read2_b32 v[6:7], v1 offset0:130 offset1:195
	v_add_u32_e32 v8, 0x400, v1
	v_add_u32_e32 v10, 0x800, v1
	v_add_u32_e32 v1, 0xc00, v1
	s_waitcnt lgkmcnt(1)
	v_cvt_pk_bf16_f32 v4, v4, v5
	s_waitcnt lgkmcnt(0)
	v_cvt_pk_bf16_f32 v5, v6, v7
	ds_read2_b32 v[6:7], v8 offset0:4 offset1:69
	ds_read2_b32 v[8:9], v8 offset0:134 offset1:199
	ds_read2_b32 v[12:13], v1 offset0:142 offset1:207
	v_readlane_b32 s12, v255, 5
	v_readlane_b32 s16, v255, 9
	s_waitcnt lgkmcnt(2)
	v_cvt_pk_bf16_f32 v6, v6, v7
	s_waitcnt lgkmcnt(1)
	v_cvt_pk_bf16_f32 v7, v8, v9
	ds_read2_b32 v[8:9], v10 offset0:8 offset1:73
	ds_read2_b32 v[10:11], v10 offset0:138 offset1:203
	v_readlane_b32 s17, v255, 10
	v_readlane_b32 s13, v255, 6
	v_readlane_b32 s14, v255, 7
	s_waitcnt lgkmcnt(1)
	v_cvt_pk_bf16_f32 v8, v8, v9
	s_waitcnt lgkmcnt(0)
	v_cvt_pk_bf16_f32 v9, v10, v11
	ds_read2_b32 v[10:11], v1 offset0:12 offset1:77
	v_subrev_u32_e32 v1, s11, v3
	v_readlane_b32 s15, v255, 8
	v_readlane_b32 s18, v255, 11
	v_readlane_b32 s19, v255, 12
	s_waitcnt lgkmcnt(0)
	v_cvt_pk_bf16_f32 v10, v10, v11
	v_cvt_pk_bf16_f32 v11, v12, v13
	v_add_u32_e32 v12, s5, v1
	v_ashrrev_i32_e32 v13, 31, v12
	v_lshlrev_b64 v[12:13], 11, v[12:13]
	v_lshl_add_u64 v[12:13], s[16:17], 0, v[12:13]
	v_lshl_add_u64 v[12:13], s[38:39], 1, v[12:13]
	v_lshl_add_u64 v[12:13], v[12:13], 0, v[182:183]
	global_store_dwordx4 v[12:13], v[4:7], off
	global_store_dwordx4 v[12:13], v[8:11], off offset:16
	s_branch .LBB0_884

; DI unsigned pk2(float a, float b) { f32x2_t f = {a, b}; return __builtin_bit_cast(unsigned, __builtin_convertvector(f, bf16x2_t)); }
; DI void tconv_tile(const float* __restrict__ src, long lds, int cvalid, u16* __restrict__ dst, long ldd, int r0, int c0, char* smem) {
;     ...
;   __syncthreads();
;   const int lr = tid >> 4, lc = (tid & 15) * 4;
; #pragma unroll
;   for (int i = 0; i < 4; ++i) {
;     const int r = lr + 16 * i;
;     float4 v = make_float4(0.f, 0.f, 0.f, 0.f);
;     if (c0 + lc < cvalid) v = *(const float4*)(src + (long)(r0 + r) * lds + c0 + lc);
;     T[r][lc] = v.x; T[r][lc + 1] = v.y; T[r][lc + 2] = v.z; T[r][lc + 3] = v.w;
;   }
;   __syncthreads();
;   const int oc = tid >> 2, seg = (tid & 3) * 16;
;   unsigned pk[8];
; #pragma unroll
;   for (int k = 0; k < 8; ++k) pk[k] = pk2(T[seg + 2 * k][oc], T[seg + 2 * k + 1][oc]);
;   uint4* d = (uint4*)(dst + (long)(c0 + oc) * ldd + r0 + seg);
;   d[0] = make_uint4(pk[0], pk[1], pk[2], pk[3]);
;   d[1] = make_uint4(pk[4], pk[5], pk[6], pk[7]);
; DI void convert_weights(const Params& p, int layer, char* smem) {
;     ...
;       } else if (t < 592) {
;         const int u = t - 448;
;         tconv_tile(p.w_q_up + (size_t)o * 384 * 1536, 1536, 1536, W + WO_Q, 384, (u / 24) * 64, (u % 24) * 64, smem);
.LBB0_1291:
	s_andn2_b64 vcc, exec, s[38:39]
	s_cbranch_vccnz .LBB0_1293
	s_add_i32 s14, s4, 64
	s_and_b32 s13, s14, 0xff
	s_mulk_i32 s13, 0xab
	s_bfe_u32 s13, s13, 0x4000c
	s_mul_i32 s15, s13, 24
	s_sub_i32 s14, s14, s15
	s_and_b32 s16, s14, 0xff
	v_readlane_b32 s40, v252, 0
	v_mov_b32_e32 v7, v185
	s_lshl_b32 s14, s16, 8
	v_readlane_b32 s44, v252, 4
	v_readlane_b32 s45, v252, 5
	v_lshlrev_b32_e32 v11, 4, v7
	s_add_u32 s14, s44, s14
	v_ashrrev_i32_e32 v2, 4, v7
	v_and_b32_e32 v182, 0xf0, v11
	s_addc_u32 s15, s45, 0
	v_lshl_add_u64 v[4:5], s[14:15], 0, v[182:183]
	v_lshl_add_u32 v12, s13, 6, v2
	s_movk_i32 s18, 0x1800
	v_mad_i64_i32 v[0:1], s[14:15], v12, s18, v[4:5]
	s_movk_i32 s17, 0x104
	s_waitcnt lgkmcnt(0)
	s_barrier
	global_load_dwordx4 v[102:105], v[0:1], off
	v_add_u32_e32 v113, 16, v12
	v_mad_i64_i32 v[100:101], s[14:15], v113, s18, v[4:5]
	global_load_dwordx4 v[116:119], v[100:101], off
	v_add_u32_e32 v130, 32, v12
	v_mad_i64_i32 v[114:115], s[14:15], v130, s18, v[4:5]
	global_load_dwordx4 v[120:123], v[114:115], off
	v_add_u32_e32 v131, 48, v12
	v_mad_i64_i32 v[128:129], s[14:15], v131, s18, v[4:5]
	global_load_dwordx4 v[124:127], v[128:129], off
	v_mad_u64_u32 v[8:9], s[14:15], v2, s17, v[182:183]
	s_nop 0
	v_add_u32_e32 v9, 0x1040, v8
	s_lshl_b32 s34, s13, 7
	v_readlane_b32 s41, v252, 1
	v_readlane_b32 s42, v252, 2
	v_readlane_b32 s43, v252, 3
	v_readlane_b32 s46, v252, 6
	v_readlane_b32 s47, v252, 7
	s_waitcnt vmcnt(3)
	ds_write2_b32 v8, v102, v103 offset1:1
	ds_write2_b32 v8, v104, v105 offset0:2 offset1:3
	v_add_u32_e32 v0, 16, v12
	s_waitcnt vmcnt(2)
	ds_write2_b32 v9, v116, v117 offset1:1
	v_add_u32_e32 v0, 0x1048, v8
	ds_write2_b32 v0, v118, v119 offset1:1
	v_add_u32_e32 v0, 32, v12
	v_add_u32_e32 v9, 0x2080, v8
	s_waitcnt vmcnt(1)
	ds_write2_b32 v9, v120, v121 offset1:1
	v_add_u32_e32 v0, 0x2088, v8
	ds_write2_b32 v0, v122, v123 offset1:1
	v_add_u32_e32 v0, 48, v12
	v_add_u32_e32 v4, 0x30c0, v8
	v_and_b32_e32 v9, 48, v11
	v_readlane_b32 s14, v252, 29
	v_readlane_b32 s15, v252, 30
	v_lshlrev_b32_e32 v182, 1, v9
	s_waitcnt vmcnt(0)
	ds_write2_b32 v4, v124, v125 offset1:1
	v_add_u32_e32 v0, 0x30c8, v8
	ds_write2_b32 v0, v126, v127 offset1:1
	v_and_b32_e32 v0, -4, v7
	v_ashrrev_i32_e32 v8, 2, v7
	v_mad_u32_u24 v7, v9, s17, v0
	s_waitcnt lgkmcnt(0)
	s_barrier
	ds_read2_b32 v[0:1], v7 offset1:65
	ds_read2_b32 v[2:3], v7 offset0:130 offset1:195
	v_add_u32_e32 v4, 0x400, v7
	v_add_u32_e32 v11, 0x800, v7
	v_add_u32_e32 v7, 0xc00, v7
	s_waitcnt lgkmcnt(1)
	v_cvt_pk_bf16_f32 v0, v0, v1
	s_waitcnt lgkmcnt(0)
	v_cvt_pk_bf16_f32 v1, v2, v3
	ds_read2_b32 v[2:3], v4 offset0:4 offset1:69
	ds_read2_b32 v[4:5], v4 offset0:134 offset1:199
	s_waitcnt lgkmcnt(1)
	v_cvt_pk_bf16_f32 v2, v2, v3
	s_waitcnt lgkmcnt(0)
	v_cvt_pk_bf16_f32 v3, v4, v5
	ds_read2_b32 v[4:5], v11 offset0:8 offset1:73
	s_waitcnt lgkmcnt(0)
	v_cvt_pk_bf16_f32 v12, v4, v5
	ds_read2_b32 v[4:5], v11 offset0:138 offset1:203
	s_waitcnt lgkmcnt(0)
	v_cvt_pk_bf16_f32 v13, v4, v5
	ds_read2_b32 v[4:5], v7 offset0:12 offset1:77
	s_waitcnt lgkmcnt(0)
	v_cvt_pk_bf16_f32 v14, v4, v5
	ds_read2_b32 v[4:5], v7 offset0:142 offset1:207
	v_lshl_add_u32 v7, s16, 6, v8
	s_waitcnt lgkmcnt(0)
	v_cvt_pk_bf16_f32 v15, v4, v5
	v_mov_b64_e32 v[4:5], s[14:15]
	s_movk_i32 s14, 0x300
	v_mad_i64_i32 v[4:5], s[14:15], v7, s14, v[4:5]
	v_lshl_add_u64 v[4:5], v[4:5], 0, s[34:35]
	v_lshl_add_u64 v[4:5], v[4:5], 0, v[182:183]
	global_store_dwordx4 v[4:5], v[0:3], off
	global_store_dwordx4 v[4:5], v[12:15], off offset:16

; DI int get_bid() { int b = blockIdx.x; asm volatile("" : "+s"(b)); return b; }
; DI unsigned pk2(float a, float b) { f32x2_t f = {a, b}; return __builtin_bit_cast(unsigned, __builtin_convertvector(f, bf16x2_t)); }
; DI void tconv_tile(const float* __restrict__ src, long lds, int cvalid, u16* __restrict__ dst, long ldd, int r0, int c0, char* smem) {
;     ...
;   __syncthreads();
;   const int lr = tid >> 4, lc = (tid & 15) * 4;
; #pragma unroll
;   for (int i = 0; i < 4; ++i) {
;     const int r = lr + 16 * i;
;     float4 v = make_float4(0.f, 0.f, 0.f, 0.f);
;     if (c0 + lc < cvalid) v = *(const float4*)(src + (long)(r0 + r) * lds + c0 + lc);
;     T[r][lc] = v.x; T[r][lc + 1] = v.y; T[r][lc + 2] = v.z; T[r][lc + 3] = v.w;
;   }
;   __syncthreads();
;   const int oc = tid >> 2, seg = (tid & 3) * 16;
;   unsigned pk[8];
; #pragma unroll
;   for (int k = 0; k < 8; ++k) pk[k] = pk2(T[seg + 2 * k][oc], T[seg + 2 * k + 1][oc]);
;   uint4* d = (uint4*)(dst + (long)(c0 + oc) * ldd + r0 + seg);
;   d[0] = make_uint4(pk[0], pk[1], pk[2], pk[3]);
;   d[1] = make_uint4(pk[4], pk[5], pk[6], pk[7]);
; DI void convert_weights(const Params& p, int layer, char* smem) {
;     ...
;     for (int t = get_bid(); t < 1920; t += gridDim.x) {
;       if (t < 1280) {
;         tconv_tile(p.w_in_even + (size_t)e * 1024 * 5120, 5120, 5120, W + WE_IN, 1024, (t / 80) * 64, (t % 80) * 64, smem);
.LBB0_1777:
	s_andn2_b64 vcc, exec, s[38:39]
	s_cbranch_vccnz .LBB0_1766
	s_mul_hi_i32 s11, s4, 0x66666667
	s_lshr_b32 s12, s11, 31
	s_ashr_i32 s11, s11, 5
	s_add_i32 s11, s11, s12
	s_mul_i32 s12, s11, 0xffffec00
	s_add_i32 s12, s5, s12
	s_ashr_i32 s13, s12, 31
	v_readlane_b32 s56, v253, 21
	s_lshl_b32 s38, s11, 6
	v_mov_b32_e32 v1, v185
	s_lshl_b64 s[12:13], s[12:13], 2
	v_readlane_b32 s70, v253, 35
	v_readlane_b32 s71, v253, 36
	v_lshlrev_b32_e32 v12, 4, v1
	s_add_u32 s12, s70, s12
	v_ashrrev_i32_e32 v3, 4, v1
	v_and_b32_e32 v182, 0xf0, v12
	s_addc_u32 s13, s71, s13
	v_lshl_add_u64 v[8:9], s[12:13], 0, v[182:183]
	v_add_u32_e32 v13, s38, v3
	s_movk_i32 s15, 0x5000
	v_mad_i64_i32 v[4:5], s[12:13], v13, s15, v[8:9]
	s_waitcnt lgkmcnt(0)
	s_barrier
	global_load_dwordx4 v[100:103], v[4:5], off
	v_add_u32_e32 v152, 16, v13
	v_mad_i64_i32 v[134:135], s[12:13], v152, s15, v[8:9]
	global_load_dwordx4 v[136:139], v[134:135], off
	v_add_u32_e32 v153, 32, v13
	v_mad_i64_i32 v[148:149], s[12:13], v153, s15, v[8:9]
	global_load_dwordx4 v[140:143], v[148:149], off
	v_add_u32_e32 v158, 48, v13
	v_mad_i64_i32 v[150:151], s[12:13], v158, s15, v[8:9]
	global_load_dwordx4 v[144:147], v[150:151], off
	s_nop 0
	s_movk_i32 s14, 0x104
	v_mad_u64_u32 v[10:11], s[12:13], v3, s14, v[182:183]
	v_add_u32_e32 v3, 16, v13
	v_and_b32_e32 v14, 48, v12
	s_mulk_i32 s11, 0x1400
	s_ashr_i32 s39, s38, 31
	v_readlane_b32 s64, v253, 29
	v_readlane_b32 s65, v253, 30
	v_readlane_b32 s66, v253, 31
	v_readlane_b32 s67, v253, 32
	v_readlane_b32 s68, v253, 33
	v_readlane_b32 s69, v253, 34
	v_lshlrev_b32_e32 v182, 1, v14
	s_mov_b32 s65, 0x2aaaaaab
	s_mov_b64 s[66:67], 0x5a8080
	s_movk_i32 s64, 0x41ff
	s_mov_b64 s[68:69], s[24:25]
	s_mov_b64 s[70:71], s[26:27]
	v_readlane_b32 s57, v253, 22
	v_readlane_b32 s58, v253, 23
	v_readlane_b32 s59, v253, 24
	v_readlane_b32 s60, v253, 25
	v_readlane_b32 s61, v253, 26
	v_readlane_b32 s62, v253, 27
	v_readlane_b32 s63, v253, 28
	s_waitcnt vmcnt(3)
	ds_write2_b32 v10, v100, v101 offset1:1
	ds_write2_b32 v10, v102, v103 offset0:2 offset1:3
	v_add_u32_e32 v3, 0x1040, v10
	s_waitcnt vmcnt(2)
	ds_write2_b32 v3, v136, v137 offset1:1
	v_add_u32_e32 v3, 0x1048, v10
	ds_write2_b32 v3, v138, v139 offset1:1
	v_add_u32_e32 v3, 32, v13
	v_add_u32_e32 v3, 0x2080, v10
	s_waitcnt vmcnt(1)
	ds_write2_b32 v3, v140, v141 offset1:1
	v_add_u32_e32 v3, 0x2088, v10
	ds_write2_b32 v3, v142, v143 offset1:1
	v_add_u32_e32 v3, 48, v13
	v_add_u32_e32 v3, 0x30c0, v10
	s_waitcnt vmcnt(0)
	ds_write2_b32 v3, v144, v145 offset1:1
	v_add_u32_e32 v3, 0x30c8, v10
	ds_write2_b32 v3, v146, v147 offset1:1
	v_ashrrev_i32_e32 v3, 2, v1
	v_and_b32_e32 v1, -4, v1
	v_mad_u32_u24 v1, v14, s14, v1
	s_waitcnt lgkmcnt(0)
	s_barrier
	ds_read2_b32 v[4:5], v1 offset1:65
	ds_read2_b32 v[6:7], v1 offset0:130 offset1:195
	v_add_u32_e32 v8, 0x400, v1
	v_add_u32_e32 v10, 0x800, v1
	v_add_u32_e32 v1, 0xc00, v1
	s_waitcnt lgkmcnt(1)
	v_cvt_pk_bf16_f32 v4, v4, v5
	s_waitcnt lgkmcnt(0)
	v_cvt_pk_bf16_f32 v5, v6, v7
	ds_read2_b32 v[6:7], v8 offset0:4 offset1:69
	ds_read2_b32 v[8:9], v8 offset0:134 offset1:199
	ds_read2_b32 v[12:13], v1 offset0:142 offset1:207
	v_readlane_b32 s12, v255, 5
	v_readlane_b32 s16, v255, 9
	s_waitcnt lgkmcnt(2)
	v_cvt_pk_bf16_f32 v6, v6, v7
	s_waitcnt lgkmcnt(1)
	v_cvt_pk_bf16_f32 v7, v8, v9
	ds_read2_b32 v[8:9], v10 offset0:8 offset1:73
	ds_read2_b32 v[10:11], v10 offset0:138 offset1:203
	v_readlane_b32 s17, v255, 10
	v_readlane_b32 s13, v255, 6
	v_readlane_b32 s14, v255, 7
	s_waitcnt lgkmcnt(1)
	v_cvt_pk_bf16_f32 v8, v8, v9
	s_waitcnt lgkmcnt(0)
	v_cvt_pk_bf16_f32 v9, v10, v11
	ds_read2_b32 v[10:11], v1 offset0:12 offset1:77
	v_subrev_u32_e32 v1, s11, v3
	v_readlane_b32 s15, v255, 8
	v_readlane_b32 s18, v255, 11
	v_readlane_b32 s19, v255, 12
	s_waitcnt lgkmcnt(0)
	v_cvt_pk_bf16_f32 v10, v10, v11
	v_cvt_pk_bf16_f32 v11, v12, v13
	v_add_u32_e32 v12, s5, v1
	v_ashrrev_i32_e32 v13, 31, v12
	v_lshlrev_b64 v[12:13], 11, v[12:13]
	v_lshl_add_u64 v[12:13], s[16:17], 0, v[12:13]
	v_lshl_add_u64 v[12:13], s[38:39], 1, v[12:13]
	v_lshl_add_u64 v[12:13], v[12:13], 0, v[182:183]
	global_store_dwordx4 v[12:13], v[4:7], off
	global_store_dwordx4 v[12:13], v[8:11], off offset:16
	s_branch .LBB0_1766
